# stack3: stack2 + attention-post reuses per-wave cached lam scalar + kernarg load batches merged at entry
# speedup vs baseline: 1.0157x; 1.0157x over previous
_Z9hymba_fwd4Args:
	s_mov_b32 s99, 0
	s_load_dwordx2 s[92:93], s[0:1], 0xb0
	s_load_dwordx4 s[84:87], s[0:1], 0xa0
	s_load_dword s3, s[0:1], 0xb8
	s_load_dwordx8 s[4:11], s[0:1], 0x80
	s_load_dwordx16 s[36:51], s[0:1], 0x0
	s_load_dwordx16 s[52:67], s[0:1], 0x40
	s_waitcnt lgkmcnt(0)
	v_writelane_b32 v247, s4, 0
	s_nop 1
	v_writelane_b32 v247, s5, 1
	v_writelane_b32 v247, s6, 2
	v_writelane_b32 v247, s7, 3
	v_writelane_b32 v247, s8, 4
	v_writelane_b32 v247, s9, 5
	v_writelane_b32 v247, s10, 6
	v_writelane_b32 v247, s11, 7
	s_add_u32 s4, s0, 0xb8
	s_addc_u32 s5, s1, 0
	v_writelane_b32 v247, s4, 8
	v_readfirstlane_b32 s6, v0
	s_nop 0
	v_writelane_b32 v247, s5, 9
	v_writelane_b32 v247, s3, 10
	s_and_b32 s3, s3, 7
	s_cmp_lg_u32 s3, 0
	v_writelane_b32 v247, s2, 11
	v_writelane_b32 v247, s2, 12
	s_cbranch_scc1 .LBB0_2
	s_load_dword s2, s[0:1], 0xb8
	v_readlane_b32 s5, v247, 11
	s_ashr_i32 s3, s5, 31
	s_lshr_b32 s3, s3, 29
	s_add_i32 s3, s5, s3
	s_and_b32 s4, s3, -8
	s_waitcnt lgkmcnt(0)
	s_ashr_i32 s2, s2, 3
	s_sub_i32 s4, s5, s4
	s_mul_i32 s2, s2, s4
	s_ashr_i32 s3, s3, 3
	s_add_i32 s2, s2, s3
	v_writelane_b32 v247, s2, 12

.LBB0_5:
	s_or_b64 exec, exec, s[2:3]
	s_add_u32 s0, s92, 0x1000
	s_addc_u32 s1, s93, 0
	v_writelane_b32 v247, s0, 13
	s_waitcnt lgkmcnt(0)
	s_barrier
	v_writelane_b32 v247, s1, 14
	s_getreg_b32 s0, hwreg(HW_REG_XCC_ID, 0, 4)
	s_and_b32 s0, s0, 15
	s_cmp_lt_u32 s6, 64
	v_writelane_b32 v247, s0, 15
	s_cselect_b64 s[0:1], -1, 0
	v_writelane_b32 v247, s0, 16
	s_cmp_gt_u32 s6, 63
	s_mov_b64 s[2:3], 0x1000
	v_writelane_b32 v247, s1, 17
	s_cbranch_scc1 .LBB0_10
	v_mbcnt_lo_u32_b32 v0, -1, 0
	v_mbcnt_hi_u32_b32 v0, -1, v0
	s_nop 0
	v_cmp_eq_u32_e32 vcc, 0, v0
	s_and_saveexec_b64 s[0:1], vcc
	s_cbranch_execz .LBB0_9
	s_mov_b64 s[4:5], exec
	v_mbcnt_lo_u32_b32 v0, s4, 0
	v_mbcnt_hi_u32_b32 v0, s5, v0
	v_cmp_eq_u32_e32 vcc, 0, v0
	s_and_b64 s[8:9], exec, vcc
	s_mov_b64 exec, s[8:9]
	s_cbranch_execz .LBB0_9
	v_readlane_b32 s7, v247, 15
	s_bcnt1_i32_b64 s4, s[4:5]
	s_lshl_b32 s7, s7, 8
	v_mov_b32_e32 v1, s4
	v_readlane_b32 s4, v247, 13
	v_mov_b32_e32 v0, s7
	v_readlane_b32 s5, v247, 14
	s_nop 4
	global_atomic_add v0, v1, s[4:5] offset:1024

.LBB0_614:
	s_waitcnt lgkmcnt(0)
	s_barrier
	ds_read_b32 v0, v38
	s_waitcnt lgkmcnt(0)
	v_readfirstlane_b32 s40, v0
	s_cmp_eq_u32 s40, 0
	s_cbranch_scc1 .LBB0_625
	s_cmp_eq_u32 s99, 0x5a5a5a5a
	s_cbranch_scc1 .Lplam_cached
	v_mbcnt_lo_u32_b32 v0, -1, 0
	v_mbcnt_hi_u32_b32 v0, -1, v0
	s_add_i32 s40, s40, -1
	v_ashrrev_i32_e32 v1, 31, v0
	v_lshl_add_u64 v[0:1], v[0:1], 2, s[52:53]
	global_load_dword v2, v[0:1], off
	v_mbcnt_lo_u32_b32 v0, -1, 0
	v_mbcnt_hi_u32_b32 v0, -1, v0
	s_nop 0
	v_ashrrev_i32_e32 v1, 31, v0
	v_lshl_add_u64 v[0:1], v[0:1], 2, s[54:55]
	global_load_dword v3, v[0:1], off
	v_mbcnt_lo_u32_b32 v0, -1, 0
	v_mbcnt_hi_u32_b32 v0, -1, v0
	s_nop 0
	v_ashrrev_i32_e32 v1, 31, v0
	v_lshl_add_u64 v[0:1], v[0:1], 2, s[56:57]
	global_load_dword v4, v[0:1], off
	v_mbcnt_lo_u32_b32 v0, -1, 0
	v_mbcnt_hi_u32_b32 v0, -1, v0
	s_nop 0
	v_ashrrev_i32_e32 v1, 31, v0
	v_lshl_add_u64 v[0:1], v[0:1], 2, s[58:59]
	global_load_dword v0, v[0:1], off
	v_mbcnt_lo_u32_b32 v1, -1, 0
	v_mbcnt_hi_u32_b32 v1, -1, v1
	s_nop 0
	v_add_u32_e32 v8, s94, v1
	s_waitcnt vmcnt(2)
	v_mul_f32_e32 v1, v2, v3
	s_nop 1
	v_mov_b32_dpp v1, v1 quad_perm:[1,0,3,2] row_mask:0xf bank_mask:0xf bound_ctrl:1
	v_fmac_f32_e32 v1, v2, v3
	v_readfirstlane_b32 s4, v8
	s_ashr_i32 s4, s4, 6
	v_add_f32_dpp v1, v1, v1 quad_perm:[2,3,0,1] row_mask:0xf bank_mask:0xf bound_ctrl:1
	s_cmp_gt_i32 s4, 15
	s_waitcnt vmcnt(0)
	v_mul_f32_e32 v3, v4, v0
	v_add_f32_dpp v1, v1, v1 row_half_mirror row_mask:0xf bank_mask:0xf bound_ctrl:1
	s_nop 0
	v_mov_b32_dpp v3, v3 quad_perm:[1,0,3,2] row_mask:0xf bank_mask:0xf bound_ctrl:1
	v_fmac_f32_e32 v3, v4, v0
	v_add_f32_dpp v1, v1, v1 row_mirror row_mask:0xf bank_mask:0xf bound_ctrl:1
	v_mov_b32_e32 v2, v1
	s_nop 1
	v_permlane16_swap_b32_e32 v1, v2
	v_add_f32_e32 v1, v1, v2
	v_mov_b32_e32 v0, v1
	v_add_f32_dpp v2, v3, v3 quad_perm:[2,3,0,1] row_mask:0xf bank_mask:0xf bound_ctrl:1
	s_nop 0
	v_permlane32_swap_b32_e32 v1, v0
	v_add_f32_dpp v2, v2, v2 row_half_mirror row_mask:0xf bank_mask:0xf bound_ctrl:1
	v_add_f32_e32 v0, v1, v0
	v_mul_f32_e32 v3, 0x3fb8aa3b, v0
	v_add_f32_dpp v1, v2, v2 row_mirror row_mask:0xf bank_mask:0xf bound_ctrl:1
	v_mov_b32_e32 v2, v1
	s_nop 1
	v_permlane16_swap_b32_e32 v1, v2
	v_fma_f32 v4, v0, s26, -v3
	v_rndne_f32_e32 v5, v3
	v_add_f32_e32 v1, v1, v2
	v_fmac_f32_e32 v4, 0x32a5705f, v0
	v_sub_f32_e32 v2, v3, v5
	v_cvt_i32_f32_e32 v3, v5
	v_mov_b32_e32 v5, v1
	v_add_f32_e32 v2, v2, v4
	s_nop 0
	v_permlane32_swap_b32_e32 v1, v5
	v_exp_f32_e32 v2, v2
	v_add_f32_e32 v1, v1, v5
	v_mul_f32_e32 v4, 0x3fb8aa3b, v1
	v_fma_f32 v5, v1, s26, -v4
	v_rndne_f32_e32 v6, v4
	v_ldexp_f32 v2, v2, v3
	v_fmac_f32_e32 v5, 0x32a5705f, v1
	v_sub_f32_e32 v3, v4, v6
	v_add_f32_e32 v3, v3, v5
	v_cvt_i32_f32_e32 v4, v6
	v_exp_f32_e32 v3, v3
	v_cmp_ngt_f32_e32 vcc, s27, v0
	s_nop 1
	v_cndmask_b32_e32 v2, 0, v2, vcc
	v_cmp_nlt_f32_e32 vcc, s28, v0
	s_nop 1
	v_cndmask_b32_e32 v0, v41, v2, vcc
	v_ldexp_f32 v2, v3, v4
	v_cmp_ngt_f32_e32 vcc, s27, v1
	s_nop 1
	v_cndmask_b32_e32 v2, 0, v2, vcc
	v_cmp_nlt_f32_e32 vcc, s28, v1
	s_nop 1
	v_cndmask_b32_e32 v1, v41, v2, vcc
	v_sub_f32_e32 v0, v0, v1
	s_nop 0
	v_readfirstlane_b32 s5, v0
	s_nop 1
	s_mov_b32 s98, s5
	s_mov_b32 s99, 0x5a5a5a5a
	s_branch .Lplam_join
.Lplam_cached:
	s_add_i32 s40, s40, -1
	v_mbcnt_lo_u32_b32 v1, -1, 0
	v_mbcnt_hi_u32_b32 v1, -1, v1
	v_add_u32_e32 v8, s94, v1
	s_nop 1
	v_readfirstlane_b32 s4, v8
	s_mov_b32 s5, s98
	s_nop 1
	s_ashr_i32 s4, s4, 6
	s_cmp_gt_i32 s4, 15
.Lplam_join:
	s_cbranch_scc1 .LBB0_618
	v_lshlrev_b32_e32 v0, 3, v8
	v_and_b32_e32 v12, 0x78, v0
	v_lshlrev_b32_e32 v4, 2, v12
	global_load_dwordx4 v[0:3], v4, s[60:61]
	s_nop 0
	global_load_dwordx4 v[4:7], v4, s[60:61] offset:16
	s_lshl_b32 s7, s40, 8
	v_add_f32_e32 v10, s5, v42
	s_lshl_b32 s5, s40, 2
	s_lshl_b32 s6, s40, 6
	s_add_i32 s41, s4, -8
	s_lshl_b32 s4, s4, 4
	s_and_b32 s7, s7, 0x1f00
	s_and_b32 s5, s5, 0x180
	s_and_b32 s6, s6, 0xffffe000
	v_or_b32_e32 v18, s5, v12
	s_add_i32 s4, s4, s7
	v_bfe_u32 v14, v8, 4, 2
	v_lshlrev_b32_e32 v8, 1, v18
	s_add_i32 s4, s4, s6
	v_mov_b32_e32 v11, v10
	v_lshl_add_u64 v[12:13], s[30:31], 0, v[8:9]
	v_or3_b32 v14, v14, s4, 12
	v_lshlrev_b32_e32 v8, 1, v18
	s_waitcnt vmcnt(1)
	v_mov_b32_e32 v16, v1
	v_mov_b32_e32 v17, v3
	v_mov_b32_e32 v1, v2
	s_waitcnt vmcnt(0)
	v_mov_b32_e32 v2, v5
	v_mov_b32_e32 v3, v7
	v_mov_b32_e32 v5, v6
